# attention: K(t+2) LDS-DMA pair issued right after the tile barrier
# speedup vs baseline: 1.0062x; 1.0009x over previous
.LBB0_185:
	s_add_i32 s100, s23, 2
	s_mov_b32 m0, s11
	s_cmp_ge_u32 s100, s17
	s_cbranch_scc1 .Lkd0
	global_load_lds_dwordx4 v214, s[80:81]
	s_add_i32 m0, s11, 0x2000
	s_nop 0
	global_load_lds_dwordx4 v214, s[62:63]

.LBB0_188:
	v_mfma_f32_32x32x16_bf16 v[34:49], v[126:129], v[162:165], v[34:49]
	ds_read_b128 v[126:129], v245 offset:16384
	s_nop 0
	v_exp_f32_e32 v130, v82
	v_exp_f32_e32 v131, v83
	v_add_f32_e32 v132, v1, v130
	v_add_f32_e32 v133, v1, v131
	v_cvt_pk_bf16_f32 v166, v130, v131
	s_waitcnt lgkmcnt(3)
	v_mfma_f32_32x32x16_bf16 v[50:65], v[122:125], v[162:165], v[50:65]
	ds_read_b128 v[122:125], v245 offset:20480
	v_exp_f32_e32 v134, v84
	v_exp_f32_e32 v135, v85
	s_add_i32 s22, s23, 2
	v_add_f32_e32 v130, v132, v134
	v_add_f32_e32 v131, v133, v135
	v_cvt_pk_bf16_f32 v167, v134, v135
.LBB0_190:
	s_waitcnt lgkmcnt(2)
	v_mfma_f32_32x32x16_bf16 v[18:33], v[118:121], v[162:165], v[18:33]
	ds_read_b128 v[118:121], v245 offset:24576
	v_exp_f32_e32 v132, v86
	v_exp_f32_e32 v133, v87
	v_add_f32_e32 v130, v130, v132
	v_add_f32_e32 v131, v131, v133
	v_cvt_pk_bf16_f32 v168, v132, v133
	v_mfma_f32_32x32x16_bf16 v[2:17], v[114:117], v[162:165], v[2:17]
	ds_read_b128 v[114:117], v245 offset:28672
	v_exp_f32_e32 v132, v88
	v_exp_f32_e32 v133, v89
	v_add_f32_e32 v134, v130, v132
	v_add_f32_e32 v131, v131, v133
	v_cvt_pk_bf16_f32 v169, v132, v133
	s_waitcnt lgkmcnt(2)
	v_mfma_f32_32x32x16_bf16 v[34:49], v[126:129], v[170:173], v[34:49]
	ds_read_b128 v[126:129], v246 offset:16384
	v_exp_f32_e32 v132, v90
	v_exp_f32_e32 v133, v91
	v_add_f32_e32 v134, v134, v132
	v_add_f32_e32 v135, v131, v133
	v_cvt_pk_bf16_f32 v174, v132, v133
	v_mfma_f32_32x32x16_bf16 v[50:65], v[122:125], v[170:173], v[50:65]
	ds_read_b128 v[122:125], v246 offset:20480
	v_exp_f32_e32 v133, v92
	v_exp_f32_e32 v136, v93
	v_add_f32_e32 v131, v134, v133
	v_add_f32_e32 v132, v135, v136
	v_cvt_pk_bf16_f32 v175, v133, v136

.LBB0_225:
	s_add_i32 s100, s23, 3
	s_add_i32 m0, s11, 0x4000
	s_cmp_gt_u32 s100, s16
	s_cbranch_scc1 .Lkd1
	global_load_lds_dwordx4 v214, s[50:51]
	s_add_i32 m0, s11, 0x6000
	s_nop 0
	global_load_lds_dwordx4 v214, s[4:5]

.LBB0_228:
	v_mfma_f32_32x32x16_bf16 v[34:49], v[126:129], v[166:169], v[34:49]
	ds_read_b128 v[126:129], v245 offset:32768
	s_nop 0
	v_exp_f32_e32 v130, v82
	v_exp_f32_e32 v131, v83
	v_add_f32_e32 v132, v1, v130
	v_add_f32_e32 v133, v1, v131
	v_cvt_pk_bf16_f32 v162, v130, v131
	s_waitcnt lgkmcnt(3)
	v_mfma_f32_32x32x16_bf16 v[50:65], v[122:125], v[166:169], v[50:65]
	ds_read_b128 v[122:125], v245 offset:36864
	v_exp_f32_e32 v130, v84
	v_exp_f32_e32 v131, v85
	s_add_i32 s23, s23, 3
	v_add_f32_e32 v132, v132, v130
	v_add_f32_e32 v133, v133, v131
	v_cvt_pk_bf16_f32 v163, v130, v131
.LBB0_230:
	s_waitcnt lgkmcnt(2)
	v_mfma_f32_32x32x16_bf16 v[18:33], v[118:121], v[166:169], v[18:33]
	ds_read_b128 v[118:121], v245 offset:40960
	v_exp_f32_e32 v134, v86
	v_exp_f32_e32 v135, v87
	v_add_f32_e32 v132, v132, v134
	v_add_f32_e32 v133, v133, v135
	v_cvt_pk_bf16_f32 v164, v134, v135
	v_mfma_f32_32x32x16_bf16 v[2:17], v[114:117], v[166:169], v[2:17]
	ds_read_b128 v[114:117], v245 offset:45056
	v_exp_f32_e32 v134, v88
	v_exp_f32_e32 v135, v89
	v_add_f32_e32 v136, v132, v134
	v_add_f32_e32 v133, v133, v135
	v_cvt_pk_bf16_f32 v165, v134, v135
	s_waitcnt lgkmcnt(2)
	v_mfma_f32_32x32x16_bf16 v[34:49], v[126:129], v[174:177], v[34:49]
	ds_read_b128 v[126:129], v246 offset:32768
	v_exp_f32_e32 v134, v90
	v_exp_f32_e32 v135, v91
	v_add_f32_e32 v136, v136, v134
	v_add_f32_e32 v137, v133, v135
	v_cvt_pk_bf16_f32 v170, v134, v135
	v_mfma_f32_32x32x16_bf16 v[50:65], v[122:125], v[174:177], v[50:65]
	ds_read_b128 v[122:125], v246 offset:36864
	v_exp_f32_e32 v135, v92
	v_exp_f32_e32 v138, v93
	v_add_f32_e32 v133, v136, v135
	v_add_f32_e32 v134, v137, v138
	v_cvt_pk_bf16_f32 v171, v135, v138

.Lr1u1_LBB0_185:
	s_add_i32 s100, s23, 2
	s_add_i32 m0, s11, 0x8000
	s_cmp_ge_u32 s100, s17
	s_cbranch_scc1 .Lkd2
	global_load_lds_dwordx4 v214, s[80:81]
	s_add_i32 m0, s11, 0xa000
	s_nop 0
	global_load_lds_dwordx4 v214, s[62:63]

.Lr1u1_LBB0_188:
	v_mfma_f32_32x32x16_bf16 v[34:49], v[126:129], v[162:165], v[34:49]
	ds_read_b128 v[126:129], v245 offset:49152
	s_nop 0
	v_exp_f32_e32 v130, v82
	v_exp_f32_e32 v131, v83
	v_add_f32_e32 v132, v1, v130
	v_add_f32_e32 v133, v1, v131
	v_cvt_pk_bf16_f32 v166, v130, v131
	s_waitcnt lgkmcnt(3)
	v_mfma_f32_32x32x16_bf16 v[50:65], v[122:125], v[162:165], v[50:65]
	ds_read_b128 v[122:125], v245 offset:53248
	v_exp_f32_e32 v134, v84
	v_exp_f32_e32 v135, v85
	s_add_i32 s22, s23, 2
	v_add_f32_e32 v130, v132, v134
	v_add_f32_e32 v131, v133, v135
	v_cvt_pk_bf16_f32 v167, v134, v135
.Lr1u1_LBB0_190:
	s_waitcnt lgkmcnt(2)
	v_mfma_f32_32x32x16_bf16 v[18:33], v[118:121], v[162:165], v[18:33]
	ds_read_b128 v[118:121], v245 offset:57344
	v_exp_f32_e32 v132, v86
	v_exp_f32_e32 v133, v87
	v_add_f32_e32 v130, v130, v132
	v_add_f32_e32 v131, v131, v133
	v_cvt_pk_bf16_f32 v168, v132, v133
	v_mfma_f32_32x32x16_bf16 v[2:17], v[114:117], v[162:165], v[2:17]
	ds_read_b128 v[114:117], v245 offset:61440
	v_exp_f32_e32 v132, v88
	v_exp_f32_e32 v133, v89
	v_add_f32_e32 v134, v130, v132
	v_add_f32_e32 v131, v131, v133
	v_cvt_pk_bf16_f32 v169, v132, v133
	s_waitcnt lgkmcnt(2)
	v_mfma_f32_32x32x16_bf16 v[34:49], v[126:129], v[170:173], v[34:49]
	ds_read_b128 v[126:129], v246 offset:49152
	v_exp_f32_e32 v132, v90
	v_exp_f32_e32 v133, v91
	v_add_f32_e32 v134, v134, v132
	v_add_f32_e32 v135, v131, v133
	v_cvt_pk_bf16_f32 v174, v132, v133
	v_mfma_f32_32x32x16_bf16 v[50:65], v[122:125], v[170:173], v[50:65]
	ds_read_b128 v[122:125], v246 offset:53248
	v_exp_f32_e32 v133, v92
	v_exp_f32_e32 v136, v93
	v_add_f32_e32 v131, v134, v133
	v_add_f32_e32 v132, v135, v136
	v_cvt_pk_bf16_f32 v175, v133, v136

.Lr1u1_LBB0_225:
	s_add_i32 s100, s23, 3
	s_mov_b32 m0, s11
	s_cmp_gt_u32 s100, s16
	s_cbranch_scc1 .Lkd3
	global_load_lds_dwordx4 v214, s[50:51]
	s_add_i32 m0, s11, 0x2000
	s_nop 0
	global_load_lds_dwordx4 v214, s[4:5]

.Lr1u1_LBB0_228:
	v_mfma_f32_32x32x16_bf16 v[34:49], v[126:129], v[166:169], v[34:49]
	ds_read_b128 v[126:129], v245 offset:16384
	s_nop 0
	v_exp_f32_e32 v130, v82
	v_exp_f32_e32 v131, v83
	v_add_f32_e32 v132, v1, v130
	v_add_f32_e32 v133, v1, v131
	v_cvt_pk_bf16_f32 v162, v130, v131
	s_waitcnt lgkmcnt(3)
	v_mfma_f32_32x32x16_bf16 v[50:65], v[122:125], v[166:169], v[50:65]
	ds_read_b128 v[122:125], v245 offset:20480
	v_exp_f32_e32 v130, v84
	v_exp_f32_e32 v131, v85
	s_add_i32 s23, s23, 3
	v_add_f32_e32 v132, v132, v130
	v_add_f32_e32 v133, v133, v131
	v_cvt_pk_bf16_f32 v163, v130, v131
.Lr1u1_LBB0_230:
	s_waitcnt lgkmcnt(2)
	v_mfma_f32_32x32x16_bf16 v[18:33], v[118:121], v[166:169], v[18:33]
	ds_read_b128 v[118:121], v245 offset:24576
	v_exp_f32_e32 v134, v86
	v_exp_f32_e32 v135, v87
	v_add_f32_e32 v132, v132, v134
	v_add_f32_e32 v133, v133, v135
	v_cvt_pk_bf16_f32 v164, v134, v135
	v_mfma_f32_32x32x16_bf16 v[2:17], v[114:117], v[166:169], v[2:17]
	ds_read_b128 v[114:117], v245 offset:28672
	v_exp_f32_e32 v134, v88
	v_exp_f32_e32 v135, v89
	v_add_f32_e32 v136, v132, v134
	v_add_f32_e32 v133, v133, v135
	v_cvt_pk_bf16_f32 v165, v134, v135
	s_waitcnt lgkmcnt(2)
	v_mfma_f32_32x32x16_bf16 v[34:49], v[126:129], v[174:177], v[34:49]
	ds_read_b128 v[126:129], v246 offset:16384
	v_exp_f32_e32 v134, v90
	v_exp_f32_e32 v135, v91
	v_add_f32_e32 v136, v136, v134
	v_add_f32_e32 v137, v133, v135
	v_cvt_pk_bf16_f32 v170, v134, v135
	v_mfma_f32_32x32x16_bf16 v[50:65], v[122:125], v[174:177], v[50:65]
	ds_read_b128 v[122:125], v246 offset:20480
	v_exp_f32_e32 v135, v92
	v_exp_f32_e32 v138, v93
	v_add_f32_e32 v133, v136, v135
	v_add_f32_e32 v134, v137, v138
	v_cvt_pk_bf16_f32 v171, v135, v138

.Lr2u1_LBB0_185:
	s_add_i32 s100, s23, 2
	s_add_i32 m0, s11, 0x4000
	s_cmp_ge_u32 s100, s17
	s_cbranch_scc1 .Lkd4
	global_load_lds_dwordx4 v214, s[80:81]
	s_add_i32 m0, s11, 0x6000
	s_nop 0
	global_load_lds_dwordx4 v214, s[62:63]

.Lr2u1_LBB0_188:
	v_mfma_f32_32x32x16_bf16 v[34:49], v[126:129], v[162:165], v[34:49]
	ds_read_b128 v[126:129], v245 offset:32768
	s_nop 0
	v_exp_f32_e32 v130, v82
	v_exp_f32_e32 v131, v83
	v_add_f32_e32 v132, v1, v130
	v_add_f32_e32 v133, v1, v131
	v_cvt_pk_bf16_f32 v166, v130, v131
	s_waitcnt lgkmcnt(3)
	v_mfma_f32_32x32x16_bf16 v[50:65], v[122:125], v[162:165], v[50:65]
	ds_read_b128 v[122:125], v245 offset:36864
	v_exp_f32_e32 v134, v84
	v_exp_f32_e32 v135, v85
	s_add_i32 s22, s23, 2
	v_add_f32_e32 v130, v132, v134
	v_add_f32_e32 v131, v133, v135
	v_cvt_pk_bf16_f32 v167, v134, v135
.Lr2u1_LBB0_190:
	s_waitcnt lgkmcnt(2)
	v_mfma_f32_32x32x16_bf16 v[18:33], v[118:121], v[162:165], v[18:33]
	ds_read_b128 v[118:121], v245 offset:40960
	v_exp_f32_e32 v132, v86
	v_exp_f32_e32 v133, v87
	v_add_f32_e32 v130, v130, v132
	v_add_f32_e32 v131, v131, v133
	v_cvt_pk_bf16_f32 v168, v132, v133
	v_mfma_f32_32x32x16_bf16 v[2:17], v[114:117], v[162:165], v[2:17]
	ds_read_b128 v[114:117], v245 offset:45056
	v_exp_f32_e32 v132, v88
	v_exp_f32_e32 v133, v89
	v_add_f32_e32 v134, v130, v132
	v_add_f32_e32 v131, v131, v133
	v_cvt_pk_bf16_f32 v169, v132, v133
	s_waitcnt lgkmcnt(2)
	v_mfma_f32_32x32x16_bf16 v[34:49], v[126:129], v[170:173], v[34:49]
	ds_read_b128 v[126:129], v246 offset:32768
	v_exp_f32_e32 v132, v90
	v_exp_f32_e32 v133, v91
	v_add_f32_e32 v134, v134, v132
	v_add_f32_e32 v135, v131, v133
	v_cvt_pk_bf16_f32 v174, v132, v133
	v_mfma_f32_32x32x16_bf16 v[50:65], v[122:125], v[170:173], v[50:65]
	ds_read_b128 v[122:125], v246 offset:36864
	v_exp_f32_e32 v133, v92
	v_exp_f32_e32 v136, v93
	v_add_f32_e32 v131, v134, v133
	v_add_f32_e32 v132, v135, v136
	v_cvt_pk_bf16_f32 v175, v133, v136

.Lr2u1_LBB0_225:
	s_add_i32 s100, s23, 3
	s_add_i32 m0, s11, 0x8000
	s_cmp_gt_u32 s100, s16
	s_cbranch_scc1 .Lkd5
	global_load_lds_dwordx4 v214, s[50:51]
	s_add_i32 m0, s11, 0xa000
	s_nop 0
	global_load_lds_dwordx4 v214, s[4:5]

.Lr2u1_LBB0_228:
	v_mfma_f32_32x32x16_bf16 v[34:49], v[126:129], v[166:169], v[34:49]
	ds_read_b128 v[126:129], v245 offset:49152
	s_nop 0
	v_exp_f32_e32 v130, v82
	v_exp_f32_e32 v131, v83
	v_add_f32_e32 v132, v1, v130
	v_add_f32_e32 v133, v1, v131
	v_cvt_pk_bf16_f32 v162, v130, v131
	s_waitcnt lgkmcnt(3)
	v_mfma_f32_32x32x16_bf16 v[50:65], v[122:125], v[166:169], v[50:65]
	ds_read_b128 v[122:125], v245 offset:53248
	v_exp_f32_e32 v130, v84
	v_exp_f32_e32 v131, v85
	s_add_i32 s23, s23, 3
	v_add_f32_e32 v132, v132, v130
	v_add_f32_e32 v133, v133, v131
	v_cvt_pk_bf16_f32 v163, v130, v131
.Lr2u1_LBB0_230:
	s_waitcnt lgkmcnt(2)
	v_mfma_f32_32x32x16_bf16 v[18:33], v[118:121], v[166:169], v[18:33]
	ds_read_b128 v[118:121], v245 offset:57344
	v_exp_f32_e32 v134, v86
	v_exp_f32_e32 v135, v87
	v_add_f32_e32 v132, v132, v134
	v_add_f32_e32 v133, v133, v135
	v_cvt_pk_bf16_f32 v164, v134, v135
	v_mfma_f32_32x32x16_bf16 v[2:17], v[114:117], v[166:169], v[2:17]
	ds_read_b128 v[114:117], v245 offset:61440
	v_exp_f32_e32 v134, v88
	v_exp_f32_e32 v135, v89
	v_add_f32_e32 v136, v132, v134
	v_add_f32_e32 v133, v133, v135
	v_cvt_pk_bf16_f32 v165, v134, v135
	s_waitcnt lgkmcnt(2)
	v_mfma_f32_32x32x16_bf16 v[34:49], v[126:129], v[174:177], v[34:49]
	ds_read_b128 v[126:129], v246 offset:49152
	v_exp_f32_e32 v134, v90
	v_exp_f32_e32 v135, v91
	v_add_f32_e32 v136, v136, v134
	v_add_f32_e32 v137, v133, v135
	v_cvt_pk_bf16_f32 v170, v134, v135
	v_mfma_f32_32x32x16_bf16 v[50:65], v[122:125], v[174:177], v[50:65]
	ds_read_b128 v[122:125], v246 offset:53248
	v_exp_f32_e32 v135, v92
	v_exp_f32_e32 v138, v93
	v_add_f32_e32 v133, v136, v135
	v_add_f32_e32 v134, v137, v138
	v_cvt_pk_bf16_f32 v171, v135, v138

.LBB0_288:
	s_add_i32 s100, s22, 2
	s_mov_b32 m0, s10
	s_cmp_ge_u32 s100, s18
	s_cbranch_scc1 .Lkd6
	global_load_lds_dwordx4 v214, s[80:81]
	s_add_i32 m0, s10, 0x2000
	s_nop 0
	global_load_lds_dwordx4 v214, s[62:63]

.LBB0_291:
	v_mfma_f32_32x32x16_bf16 v[50:65], v[126:129], v[162:165], v[50:65]
	ds_read_b128 v[126:129], v246 offset:16384
	s_nop 1
	v_exp_f32_e32 v130, v82
	v_exp_f32_e32 v131, v83
	v_add_f32_e32 v132, v1, v130
	v_add_f32_e32 v133, v1, v131
	v_cvt_pk_bf16_f32 v166, v130, v131
	s_waitcnt lgkmcnt(3)
	v_mfma_f32_32x32x16_bf16 v[34:49], v[122:125], v[162:165], v[34:49]
	ds_read_b128 v[122:125], v246 offset:20480
	v_exp_f32_e32 v134, v84
	v_exp_f32_e32 v135, v85
	s_add_i32 s21, s22, 2
	v_add_f32_e32 v130, v132, v134
	v_add_f32_e32 v131, v133, v135
	v_cvt_pk_bf16_f32 v167, v134, v135
.LBB0_293:
	s_waitcnt lgkmcnt(2)
	v_mfma_f32_32x32x16_bf16 v[18:33], v[118:121], v[162:165], v[18:33]
	ds_read_b128 v[118:121], v246 offset:24576
	v_exp_f32_e32 v132, v86
	v_exp_f32_e32 v133, v87
	v_add_f32_e32 v130, v130, v132
	v_add_f32_e32 v131, v131, v133
	v_cvt_pk_bf16_f32 v168, v132, v133
	v_mfma_f32_32x32x16_bf16 v[2:17], v[114:117], v[162:165], v[2:17]
	ds_read_b128 v[114:117], v246 offset:28672
	v_exp_f32_e32 v0, v88
	v_exp_f32_e32 v132, v89
	v_add_f32_e32 v130, v130, v0
	v_add_f32_e32 v131, v131, v132
	v_cvt_pk_bf16_f32 v169, v0, v132
	s_waitcnt lgkmcnt(2)
	v_mfma_f32_32x32x16_bf16 v[50:65], v[126:129], v[170:173], v[50:65]
	ds_read_b128 v[126:129], v247 offset:16384
	v_exp_f32_e32 v132, v90
	v_exp_f32_e32 v133, v91
	v_add_f32_e32 v130, v130, v132
	v_add_f32_e32 v131, v131, v133
	v_cvt_pk_bf16_f32 v174, v132, v133
	v_mfma_f32_32x32x16_bf16 v[34:49], v[122:125], v[170:173], v[34:49]
	ds_read_b128 v[122:125], v247 offset:20480
	v_exp_f32_e32 v132, v92
	v_exp_f32_e32 v133, v93
	v_add_f32_e32 v130, v130, v132
	v_add_f32_e32 v131, v131, v133
	v_cvt_pk_bf16_f32 v175, v132, v133

.LBB0_328:
	s_add_i32 s100, s22, 3
	s_add_i32 m0, s10, 0x4000
	s_cmp_gt_u32 s100, s17
	s_cbranch_scc1 .Lkd7
	global_load_lds_dwordx4 v214, s[50:51]
	s_add_i32 m0, s10, 0x6000
	s_nop 0
	global_load_lds_dwordx4 v214, s[4:5]

.LBB0_331:
	v_mfma_f32_32x32x16_bf16 v[50:65], v[126:129], v[166:169], v[50:65]
	ds_read_b128 v[126:129], v246 offset:32768
	s_nop 0
	v_exp_f32_e32 v130, v82
	v_exp_f32_e32 v131, v83
	v_add_f32_e32 v132, v1, v130
	v_add_f32_e32 v133, v1, v131
	v_cvt_pk_bf16_f32 v162, v130, v131
	s_waitcnt lgkmcnt(3)
	v_mfma_f32_32x32x16_bf16 v[34:49], v[122:125], v[166:169], v[34:49]
	ds_read_b128 v[122:125], v246 offset:36864
	v_exp_f32_e32 v130, v84
	v_exp_f32_e32 v131, v85
	s_add_i32 s22, s22, 3
	v_add_f32_e32 v132, v132, v130
	v_add_f32_e32 v133, v133, v131
	v_cvt_pk_bf16_f32 v163, v130, v131
.LBB0_333:
	s_waitcnt lgkmcnt(2)
	v_mfma_f32_32x32x16_bf16 v[18:33], v[118:121], v[166:169], v[18:33]
	ds_read_b128 v[118:121], v246 offset:40960
	v_exp_f32_e32 v134, v86
	v_exp_f32_e32 v135, v87
	v_add_f32_e32 v132, v132, v134
	v_add_f32_e32 v133, v133, v135
	v_cvt_pk_bf16_f32 v164, v134, v135
	v_mfma_f32_32x32x16_bf16 v[2:17], v[114:117], v[166:169], v[2:17]
	ds_read_b128 v[114:117], v246 offset:45056
	v_exp_f32_e32 v0, v88
	v_exp_f32_e32 v134, v89
	v_add_f32_e32 v132, v132, v0
	v_add_f32_e32 v133, v133, v134
	v_cvt_pk_bf16_f32 v165, v0, v134
	s_waitcnt lgkmcnt(2)
	v_mfma_f32_32x32x16_bf16 v[50:65], v[126:129], v[174:177], v[50:65]
	ds_read_b128 v[126:129], v247 offset:32768
	v_exp_f32_e32 v134, v90
	v_exp_f32_e32 v135, v91
	v_add_f32_e32 v132, v132, v134
	v_add_f32_e32 v133, v133, v135
	v_cvt_pk_bf16_f32 v170, v134, v135
	v_mfma_f32_32x32x16_bf16 v[34:49], v[122:125], v[174:177], v[34:49]
	ds_read_b128 v[122:125], v247 offset:36864
	v_exp_f32_e32 v134, v92
	v_exp_f32_e32 v135, v93
	v_add_f32_e32 v132, v132, v134
	v_add_f32_e32 v133, v133, v135
	v_cvt_pk_bf16_f32 v171, v134, v135

.Lr1u2_LBB0_288:
	s_add_i32 s100, s22, 2
	s_add_i32 m0, s10, 0x8000
	s_cmp_ge_u32 s100, s18
	s_cbranch_scc1 .Lkd8
	global_load_lds_dwordx4 v214, s[80:81]
	s_add_i32 m0, s10, 0xa000
	s_nop 0
	global_load_lds_dwordx4 v214, s[62:63]

.Lr1u2_LBB0_291:
	v_mfma_f32_32x32x16_bf16 v[50:65], v[126:129], v[162:165], v[50:65]
	ds_read_b128 v[126:129], v246 offset:49152
	s_nop 1
	v_exp_f32_e32 v130, v82
	v_exp_f32_e32 v131, v83
	v_add_f32_e32 v132, v1, v130
	v_add_f32_e32 v133, v1, v131
	v_cvt_pk_bf16_f32 v166, v130, v131
	s_waitcnt lgkmcnt(3)
	v_mfma_f32_32x32x16_bf16 v[34:49], v[122:125], v[162:165], v[34:49]
	ds_read_b128 v[122:125], v246 offset:53248
	v_exp_f32_e32 v134, v84
	v_exp_f32_e32 v135, v85
	s_add_i32 s21, s22, 2
	v_add_f32_e32 v130, v132, v134
	v_add_f32_e32 v131, v133, v135
	v_cvt_pk_bf16_f32 v167, v134, v135
.Lr1u2_LBB0_293:
	s_waitcnt lgkmcnt(2)
	v_mfma_f32_32x32x16_bf16 v[18:33], v[118:121], v[162:165], v[18:33]
	ds_read_b128 v[118:121], v246 offset:57344
	v_exp_f32_e32 v132, v86
	v_exp_f32_e32 v133, v87
	v_add_f32_e32 v130, v130, v132
	v_add_f32_e32 v131, v131, v133
	v_cvt_pk_bf16_f32 v168, v132, v133
	v_mfma_f32_32x32x16_bf16 v[2:17], v[114:117], v[162:165], v[2:17]
	ds_read_b128 v[114:117], v246 offset:61440
	v_exp_f32_e32 v0, v88
	v_exp_f32_e32 v132, v89
	v_add_f32_e32 v130, v130, v0
	v_add_f32_e32 v131, v131, v132
	v_cvt_pk_bf16_f32 v169, v0, v132
	s_waitcnt lgkmcnt(2)
	v_mfma_f32_32x32x16_bf16 v[50:65], v[126:129], v[170:173], v[50:65]
	ds_read_b128 v[126:129], v247 offset:49152
	v_exp_f32_e32 v132, v90
	v_exp_f32_e32 v133, v91
	v_add_f32_e32 v130, v130, v132
	v_add_f32_e32 v131, v131, v133
	v_cvt_pk_bf16_f32 v174, v132, v133
	v_mfma_f32_32x32x16_bf16 v[34:49], v[122:125], v[170:173], v[34:49]
	ds_read_b128 v[122:125], v247 offset:53248
	v_exp_f32_e32 v132, v92
	v_exp_f32_e32 v133, v93
	v_add_f32_e32 v130, v130, v132
	v_add_f32_e32 v131, v131, v133
	v_cvt_pk_bf16_f32 v175, v132, v133

.Lr1u2_LBB0_328:
	s_add_i32 s100, s22, 3
	s_mov_b32 m0, s10
	s_cmp_gt_u32 s100, s17
	s_cbranch_scc1 .Lkd9
	global_load_lds_dwordx4 v214, s[50:51]
	s_add_i32 m0, s10, 0x2000
	s_nop 0
	global_load_lds_dwordx4 v214, s[4:5]

.Lr1u2_LBB0_331:
	v_mfma_f32_32x32x16_bf16 v[50:65], v[126:129], v[166:169], v[50:65]
	ds_read_b128 v[126:129], v246 offset:16384
	s_nop 0
	v_exp_f32_e32 v130, v82
	v_exp_f32_e32 v131, v83
	v_add_f32_e32 v132, v1, v130
	v_add_f32_e32 v133, v1, v131
	v_cvt_pk_bf16_f32 v162, v130, v131
	s_waitcnt lgkmcnt(3)
	v_mfma_f32_32x32x16_bf16 v[34:49], v[122:125], v[166:169], v[34:49]
	ds_read_b128 v[122:125], v246 offset:20480
	v_exp_f32_e32 v130, v84
	v_exp_f32_e32 v131, v85
	s_add_i32 s22, s22, 3
	v_add_f32_e32 v132, v132, v130
	v_add_f32_e32 v133, v133, v131
	v_cvt_pk_bf16_f32 v163, v130, v131
.Lr1u2_LBB0_333:
	s_waitcnt lgkmcnt(2)
	v_mfma_f32_32x32x16_bf16 v[18:33], v[118:121], v[166:169], v[18:33]
	ds_read_b128 v[118:121], v246 offset:24576
	v_exp_f32_e32 v134, v86
	v_exp_f32_e32 v135, v87
	v_add_f32_e32 v132, v132, v134
	v_add_f32_e32 v133, v133, v135
	v_cvt_pk_bf16_f32 v164, v134, v135
	v_mfma_f32_32x32x16_bf16 v[2:17], v[114:117], v[166:169], v[2:17]
	ds_read_b128 v[114:117], v246 offset:28672
	v_exp_f32_e32 v0, v88
	v_exp_f32_e32 v134, v89
	v_add_f32_e32 v132, v132, v0
	v_add_f32_e32 v133, v133, v134
	v_cvt_pk_bf16_f32 v165, v0, v134
	s_waitcnt lgkmcnt(2)
	v_mfma_f32_32x32x16_bf16 v[50:65], v[126:129], v[174:177], v[50:65]
	ds_read_b128 v[126:129], v247 offset:16384
	v_exp_f32_e32 v134, v90
	v_exp_f32_e32 v135, v91
	v_add_f32_e32 v132, v132, v134
	v_add_f32_e32 v133, v133, v135
	v_cvt_pk_bf16_f32 v170, v134, v135
	v_mfma_f32_32x32x16_bf16 v[34:49], v[122:125], v[174:177], v[34:49]
	ds_read_b128 v[122:125], v247 offset:20480
	v_exp_f32_e32 v134, v92
	v_exp_f32_e32 v135, v93
	v_add_f32_e32 v132, v132, v134
	v_add_f32_e32 v133, v133, v135
	v_cvt_pk_bf16_f32 v171, v134, v135

.Lr2u2_LBB0_288:
	s_add_i32 s100, s22, 2
	s_add_i32 m0, s10, 0x4000
	s_cmp_ge_u32 s100, s18
	s_cbranch_scc1 .Lkd10
	global_load_lds_dwordx4 v214, s[80:81]
	s_add_i32 m0, s10, 0x6000
	s_nop 0
	global_load_lds_dwordx4 v214, s[62:63]

.Lr2u2_LBB0_291:
	v_mfma_f32_32x32x16_bf16 v[50:65], v[126:129], v[162:165], v[50:65]
	ds_read_b128 v[126:129], v246 offset:32768
	s_nop 1
	v_exp_f32_e32 v130, v82
	v_exp_f32_e32 v131, v83
	v_add_f32_e32 v132, v1, v130
	v_add_f32_e32 v133, v1, v131
	v_cvt_pk_bf16_f32 v166, v130, v131
	s_waitcnt lgkmcnt(3)
	v_mfma_f32_32x32x16_bf16 v[34:49], v[122:125], v[162:165], v[34:49]
	ds_read_b128 v[122:125], v246 offset:36864
	v_exp_f32_e32 v134, v84
	v_exp_f32_e32 v135, v85
	s_add_i32 s21, s22, 2
	v_add_f32_e32 v130, v132, v134
	v_add_f32_e32 v131, v133, v135
	v_cvt_pk_bf16_f32 v167, v134, v135
.Lr2u2_LBB0_293:
	s_waitcnt lgkmcnt(2)
	v_mfma_f32_32x32x16_bf16 v[18:33], v[118:121], v[162:165], v[18:33]
	ds_read_b128 v[118:121], v246 offset:40960
	v_exp_f32_e32 v132, v86
	v_exp_f32_e32 v133, v87
	v_add_f32_e32 v130, v130, v132
	v_add_f32_e32 v131, v131, v133
	v_cvt_pk_bf16_f32 v168, v132, v133
	v_mfma_f32_32x32x16_bf16 v[2:17], v[114:117], v[162:165], v[2:17]
	ds_read_b128 v[114:117], v246 offset:45056
	v_exp_f32_e32 v0, v88
	v_exp_f32_e32 v132, v89
	v_add_f32_e32 v130, v130, v0
	v_add_f32_e32 v131, v131, v132
	v_cvt_pk_bf16_f32 v169, v0, v132
	s_waitcnt lgkmcnt(2)
	v_mfma_f32_32x32x16_bf16 v[50:65], v[126:129], v[170:173], v[50:65]
	ds_read_b128 v[126:129], v247 offset:32768
	v_exp_f32_e32 v132, v90
	v_exp_f32_e32 v133, v91
	v_add_f32_e32 v130, v130, v132
	v_add_f32_e32 v131, v131, v133
	v_cvt_pk_bf16_f32 v174, v132, v133
	v_mfma_f32_32x32x16_bf16 v[34:49], v[122:125], v[170:173], v[34:49]
	ds_read_b128 v[122:125], v247 offset:36864
	v_exp_f32_e32 v132, v92
	v_exp_f32_e32 v133, v93
	v_add_f32_e32 v130, v130, v132
	v_add_f32_e32 v131, v131, v133
	v_cvt_pk_bf16_f32 v175, v132, v133

.Lr2u2_LBB0_328:
	s_add_i32 s100, s22, 3
	s_add_i32 m0, s10, 0x8000
	s_cmp_gt_u32 s100, s17
	s_cbranch_scc1 .Lkd11
	global_load_lds_dwordx4 v214, s[50:51]
	s_add_i32 m0, s10, 0xa000
	s_nop 0
	global_load_lds_dwordx4 v214, s[4:5]

.Lr2u2_LBB0_331:
	v_mfma_f32_32x32x16_bf16 v[50:65], v[126:129], v[166:169], v[50:65]
	ds_read_b128 v[126:129], v246 offset:49152
	s_nop 0
	v_exp_f32_e32 v130, v82
	v_exp_f32_e32 v131, v83
	v_add_f32_e32 v132, v1, v130
	v_add_f32_e32 v133, v1, v131
	v_cvt_pk_bf16_f32 v162, v130, v131
	s_waitcnt lgkmcnt(3)
	v_mfma_f32_32x32x16_bf16 v[34:49], v[122:125], v[166:169], v[34:49]
	ds_read_b128 v[122:125], v246 offset:53248
	v_exp_f32_e32 v130, v84
	v_exp_f32_e32 v131, v85
	s_add_i32 s22, s22, 3
	v_add_f32_e32 v132, v132, v130
	v_add_f32_e32 v133, v133, v131
	v_cvt_pk_bf16_f32 v163, v130, v131
.Lr2u2_LBB0_333:
	s_waitcnt lgkmcnt(2)
	v_mfma_f32_32x32x16_bf16 v[18:33], v[118:121], v[166:169], v[18:33]
	ds_read_b128 v[118:121], v246 offset:57344
	v_exp_f32_e32 v134, v86
	v_exp_f32_e32 v135, v87
	v_add_f32_e32 v132, v132, v134
	v_add_f32_e32 v133, v133, v135
	v_cvt_pk_bf16_f32 v164, v134, v135
	v_mfma_f32_32x32x16_bf16 v[2:17], v[114:117], v[166:169], v[2:17]
	ds_read_b128 v[114:117], v246 offset:61440
	v_exp_f32_e32 v0, v88
	v_exp_f32_e32 v134, v89
	v_add_f32_e32 v132, v132, v0
	v_add_f32_e32 v133, v133, v134
	v_cvt_pk_bf16_f32 v165, v0, v134
	s_waitcnt lgkmcnt(2)
	v_mfma_f32_32x32x16_bf16 v[50:65], v[126:129], v[174:177], v[50:65]
	ds_read_b128 v[126:129], v247 offset:49152
	v_exp_f32_e32 v134, v90
	v_exp_f32_e32 v135, v91
	v_add_f32_e32 v132, v132, v134
	v_add_f32_e32 v133, v133, v135
	v_cvt_pk_bf16_f32 v170, v134, v135
	v_mfma_f32_32x32x16_bf16 v[34:49], v[122:125], v[174:177], v[34:49]
	ds_read_b128 v[122:125], v247 offset:53248
	v_exp_f32_e32 v134, v92
	v_exp_f32_e32 v135, v93
	v_add_f32_e32 v132, v132, v134
	v_add_f32_e32 v133, v133, v135
	v_cvt_pk_bf16_f32 v171, v134, v135
